# v57: IN column-tile index rotated (pn+1 mod 13; sample row tiles pn+6) so each XCD round is homogeneous in epilogue cost and the partial last round holds plain-store tiles
# baseline (speedup 1.0000x reference)
; #define PG8_WAIT_V(n) asm volatile("s_waitcnt vmcnt(" #n ")" ::: "memory")
; #define PG8_BAR __builtin_amdgcn_s_barrier()
;     __device__ __forceinline__ bool next(int i, int& pm, int& pn, int& k0, int& nk, int& slice, int& src) const {
;         const long L = (long)i * G + c;
;         pm = 0; pn = 0; k0 = 0; nk = nt; slice = -1; src = 0;
;         if (L < nwg) {
;             int wgid = (int)L; { const int q = nwg / NXCD, r = nwg % NXCD, xcd = wgid % NXCD, off = wgid / NXCD; wgid = (xcd < r ? xcd * (q + 1) : r * (q + 1) + (xcd - r) * q) + off; }
;             const int nig = WGM * nN, gid = wgid / nig, fm = gid * WGM, gsz = (nM - fm) < WGM ? (nM - fm) : WGM;
;             pm = fm + ((wgid % nig) % gsz); pn = (wgid % nig) / gsz; return true;
; template <int EPI> ...
;     ...
;     unsigned voff[2];
; #pragma unroll
;     for (int i = 0; i < 2; ++i) { int R, C; stage_rc(tid * 16 + i * 8192, R, C); voff[i] = (unsigned)(R * K + C) * 2u; }
;     const size_t kstep = (size_t)(BK * 2);
;     const size_t hstep = (size_t)HALF * K * 2;
;     const size_t tstep = 2 * hstep;
;     const unsigned ldsw = (unsigned)wid * 1024u;
;     const int aoff = lds_byte(wr * 64 + fr, fq * 8), boff = lds_byte(wc * 32 + fr, fq * 8);
;     ...
;     int ui = 0, cur_pm, cur_pn, cur_k0, cur_nk, cur_slice, cur_src, nxt_pm, nxt_pn, nxt_k0, nxt_nk, nxt_slice, nxt_src;
;     if (!S.next(0, cur_pm, cur_pn, cur_k0, cur_nk, cur_slice, cur_src)) return;
;     f32x4 acc[2][2][4][2];
; #pragma unroll
;     for (int a = 0; a < 2; ++a)
; #pragma unroll
;         for (int b = 0; b < 2; ++b)
; #pragma unroll
;             for (int m = 0; m < 4; ++m)
; #pragma unroll
;                 for (int n = 0; n < 2; ++n) acc[a][b][m][n] = (f32x4){0.f, 0.f, 0.f, 0.f};
;     bf16x8 At[4][2], B0[2][2], B1[2][2];
;     const char* cA = (const char*)((EPI == EPI_GLU && cur_src) ? gA2 : gA) + (size_t)cur_pm * tstep + (size_t)cur_k0 * kstep;
;     const char* cB = (const char*)((EPI == EPI_GLU && cur_src) ? gBt2 : gBt) + (size_t)cur_pn * tstep + (size_t)cur_k0 * kstep;
;     PG8_STAGE(PG8_SB(0, 0), cB); PG8_STAGE(PG8_SB(0, 1), cB + hstep); PG8_STAGE(PG8_SA(0, 0), cA); PG8_STAGE(PG8_SA(0, 1), cA + hstep);
;     if (wr == 1) PG8_BAR;
;     PG8_WAIT_V(2); PG8_BAR;
;     PG8_STAGE(PG8_SB(1, 0), cB + kstep); PG8_STAGE(PG8_SA(1, 0), cA + kstep); PG8_STAGE(PG8_SB(1, 1), cB + hstep + kstep);
;     PG8_WAIT_V(6); PG8_BAR;
.LBB0_123:
	s_ashr_i32 s3, s3, 3
	s_add_i32 s3, s7, s3
	s_mul_hi_i32 s4, s3, 0x4ec4ec4f
	s_lshr_b32 s5, s4, 31
	s_ashr_i32 s4, s4, 5
	s_add_i32 s4, s4, s5
	s_lshl_b32 s6, s4, 3
	s_sub_i32 s5, 0x42, s6
	s_mulk_i32 s4, 0x68
	s_min_u32 s7, s5, 8
	s_sub_i32 s3, s3, s4
	s_sext_i32_i8 s4, s3
	v_cvt_f32_ubyte0_e32 v3, s7
	v_cvt_f32_i32_e32 v2, s4
	v_rcp_iflag_f32_e32 v4, v3
	s_ashr_i32 s4, s4, 30
	s_or_b32 s8, s4, 1
	v_mul_f32_e32 v4, v2, v4
	v_trunc_f32_e32 v4, v4
	v_fma_f32 v2, -v4, v3, v2
	v_cvt_i32_f32_e32 v4, v4
	v_cmp_ge_f32_e64 s[4:5], |v2|, v3
	s_and_b64 s[4:5], s[4:5], exec
	s_cselect_b32 s4, s8, 0
	v_readfirstlane_b32 s5, v4
	s_add_i32 s5, s5, s4
	s_sext_i32_i8 s4, s5
	s_mul_i32 s5, s5, s7
	s_sub_i32 s3, s3, s5
	s_sext_i32_i8 s3, s3
	s_add_i32 s6, s6, s3
	s_cmp_ge_i32 s6, 64
	s_cselect_b32 s98, 6, 1
	s_add_i32 s4, s4, s98
	s_cmp_ge_i32 s4, 13
	s_cbranch_scc0 .Lrota
	s_sub_i32 s4, s4, 13
.Lrota:
.LBB0_124:
	s_andn2_b64 vcc, exec, s[0:1]
	v_readlane_b32 s0, v244, 33
	s_ashr_i32 s0, s0, 31
	s_nop 0
	v_writelane_b32 v244, s0, 59
	s_cbranch_vccnz .LBB0_448
	v_ashrrev_i32_e32 v3, 31, v10
	v_lshrrev_b32_e32 v3, 26, v3
	v_add_u32_e32 v3, v10, v3
	v_ashrrev_i32_e32 v11, 6, v3
	v_bfe_i32 v3, v10, 27, 1
	v_lshlrev_b32_e32 v2, 4, v10
	v_lshrrev_b32_e32 v3, 22, v3
	v_add_u32_e32 v3, v2, v3
	v_and_b32_e32 v3, 0xfffffc00, v3
	v_sub_u32_e32 v3, v2, v3
	v_lshrrev_b32_e32 v4, 4, v3
	v_bitop3_b32 v3, v4, v3, 32 bitop3:0x6c
	v_ashrrev_i32_e32 v5, 31, v3
	v_lshrrev_b32_e32 v5, 26, v5
	v_add_u32_e32 v5, v3, v5
	v_ashrrev_i32_e32 v12, 6, v5
	v_and_b32_e32 v5, 0xc0, v5
	v_sub_u32_e32 v3, v3, v5
	v_mov_b32_e32 v5, 1
	v_lshlrev_b32_e32 v4, 3, v11
	v_lshlrev_b32_e32 v6, 5, v11
	v_ashrrev_i16_sdwa v3, v5, sext(v3) dst_sel:DWORD dst_unused:UNUSED_PAD src0_sel:DWORD src1_sel:BYTE_0
	v_and_b32_e32 v4, 0x1ffff0, v4
	v_and_b32_e32 v6, 32, v6
	v_bfe_i32 v13, v3, 0, 16
	v_add_u32_e32 v3, v6, v13
	v_add_lshl_u32 v4, v12, v4, 11
	v_add_u32_e32 v2, 0x2000, v2
	v_lshl_add_u32 v136, v3, 1, v4
	v_ashrrev_i32_e32 v3, 31, v2
	v_lshrrev_b32_e32 v3, 22, v3
	v_add_u32_e32 v3, v2, v3
	v_ashrrev_i32_e32 v14, 10, v3
	v_mul_i32_i24_e32 v3, 0x400, v14
	v_sub_u32_e32 v2, v2, v3
	v_lshrrev_b32_e32 v3, 4, v2
	v_readlane_b32 s8, v244, 0
	v_bitop3_b32 v2, v3, v2, 32 bitop3:0x6c
	v_readlane_b32 s10, v244, 2
	v_ashrrev_i32_e32 v4, 31, v2
	v_readlane_b32 s11, v244, 3
	s_add_u32 s3, s10, 0xc600000
	v_lshrrev_b32_e32 v4, 26, v4
	v_readlane_b32 s9, v244, 1
	s_addc_u32 s40, s11, 0
	v_add_u32_e32 v4, v2, v4
	s_ashr_i32 s1, s12, 6
	s_ashr_i32 s7, s6, 31
	s_ashr_i32 s5, s4, 31
	s_ashr_i32 s0, s12, 8
	v_ashrrev_i32_e32 v15, 6, v4
	v_and_b32_e32 v4, 0xc0, v4
	s_lshl_b32 s41, s1, 10
	s_lshl_b64 s[8:9], s[6:7], 19
	s_lshl_b64 s[10:11], s[4:5], 19
	v_sub_u32_e32 v2, v2, v4
	s_add_u32 s28, s3, s10
	v_lshlrev_b32_e32 v3, 3, v14
	v_lshlrev_b32_e32 v6, 5, v14
	v_ashrrev_i16_sdwa v2, v5, sext(v2) dst_sel:DWORD dst_unused:UNUSED_PAD src0_sel:DWORD src1_sel:BYTE_0
	s_addc_u32 s29, s40, s11
	s_add_i32 s42, s41, 0
	v_and_b32_e32 v3, 0x1ffff0, v3
	v_and_b32_e32 v6, 32, v6
	v_bfe_i32 v16, v2, 0, 16
	s_add_i32 m0, s42, 0x10000
	v_add_u32_e32 v2, v6, v16
	v_add_lshl_u32 v3, v15, v3, 11
	global_load_lds_dwordx4 v136, s[28:29]
	s_add_i32 m0, s42, 0x12000
	v_lshl_add_u32 v138, v2, 1, v3
	s_add_u32 s10, s28, 0x40000
	global_load_lds_dwordx4 v138, s[28:29]
	s_addc_u32 s11, s29, 0
	s_add_i32 m0, s42, 0x14000
	v_mov_b32_e32 v141, 0
	global_load_lds_dwordx4 v136, s[10:11]
	s_add_i32 m0, s42, 0x16000
	s_add_u32 s26, s96, s8
	s_addc_u32 s27, s97, s9
	s_add_i32 s43, s42, 0x2000
	global_load_lds_dwordx4 v138, s[10:11]
	s_mov_b32 m0, s42
	s_add_u32 s8, s26, 0x40000
	global_load_lds_dwordx4 v136, s[26:27]
	s_mov_b32 m0, s43
	s_addc_u32 s9, s27, 0
	s_add_i32 s44, s42, 0x4000
	global_load_lds_dwordx4 v138, s[26:27]
	s_mov_b32 m0, s44
	s_add_i32 s45, s42, 0x6000
	global_load_lds_dwordx4 v136, s[8:9]
	s_mov_b32 m0, s45
	v_mov_b32_e32 v137, v141
	global_load_lds_dwordx4 v138, s[8:9]
	v_mov_b32_e32 v139, v141
	s_cmp_eq_u32 s0, 1
	s_mov_b32 s46, 0
	v_lshl_add_u64 v[8:9], s[28:29], 0, v[136:137]
	v_lshl_add_u64 v[6:7], s[28:29], 0, v[138:139]
	v_lshl_add_u64 v[2:3], s[26:27], 0, v[136:137]
	s_cselect_b64 s[8:9], -1, 0
	s_cmp_lg_u32 s0, 1
	v_lshl_add_u64 v[4:5], s[26:27], 0, v[138:139]
	s_cbranch_scc1 .LBB0_127
	s_barrier

;     __device__ __forceinline__ bool next(int i, int& pm, int& pn, int& k0, int& nk, int& slice, int& src) const {
;         const long L = (long)i * G + c;
;         pm = 0; pn = 0; k0 = 0; nk = nt; slice = -1; src = 0;
;         if (L < nwg) {
;             int wgid = (int)L; { const int q = nwg / NXCD, r = nwg % NXCD, xcd = wgid % NXCD, off = wgid / NXCD; wgid = (xcd < r ? xcd * (q + 1) : r * (q + 1) + (xcd - r) * q) + off; }
;             const int nig = WGM * nN, gid = wgid / nig, fm = gid * WGM, gsz = (nM - fm) < WGM ? (nM - fm) : WGM;
;             pm = fm + ((wgid % nig) % gsz); pn = (wgid % nig) / gsz; return true;
; template <int EPI> ...
;     ...
; #pragma unroll
;         for (int a = 0; a < 2; ++a)
; #pragma unroll
;             for (int b = 0; b < 2; ++b)
; #pragma unroll
;                 for (int m = 0; m < 4; ++m)
; #pragma unroll
;                     for (int n = 0; n < 2; ++n) acc[a][b][m][n] = (f32x4){0.f, 0.f, 0.f, 0.f};
;         cur_pm = nxt_pm; cur_pn = nxt_pn; cur_k0 = nxt_k0; cur_nk = nxt_nk; cur_slice = nxt_slice; cur_src = nxt_src; cA = nA; cB = nB; ++ui;
.LBB0_135:
	s_ashr_i32 s5, s5, 3
	s_add_i32 s5, s20, s5
	s_mul_hi_i32 s7, s5, 0x4ec4ec4f
	s_lshr_b32 s18, s7, 31
	s_ashr_i32 s7, s7, 5
	s_add_i32 s7, s7, s18
	s_lshl_b32 s19, s7, 3
	s_sub_i32 s18, 0x42, s19
	s_min_i32 s20, s18, 8
	s_abs_i32 s18, s20
	v_cvt_f32_u32_e32 v2, s18
	s_sub_i32 s22, 0, s18
	s_mulk_i32 s7, 0x68
	s_sub_i32 s5, s5, s7
	v_rcp_iflag_f32_e32 v2, v2
	s_abs_i32 s7, s5
	s_xor_b32 s21, s5, s20
	s_ashr_i32 s21, s21, 31
	v_mul_f32_e32 v2, 0x4f7ffffe, v2
	v_cvt_u32_f32_e32 v2, v2
	s_nop 0
	v_readfirstlane_b32 s23, v2
	s_mul_i32 s22, s22, s23
	s_mul_hi_u32 s22, s23, s22
	s_add_i32 s23, s23, s22
	s_mul_hi_u32 s22, s7, s23
	s_mul_i32 s23, s22, s18
	s_sub_i32 s7, s7, s23
	s_add_i32 s24, s22, 1
	s_sub_i32 s23, s7, s18
	s_cmp_ge_u32 s7, s18
	s_cselect_b32 s22, s24, s22
	s_cselect_b32 s7, s23, s7
	s_add_i32 s23, s22, 1
	s_cmp_ge_u32 s7, s18
	s_cselect_b32 s7, s23, s22
	s_xor_b32 s7, s7, s21
	s_sub_i32 s18, s7, s21
	s_mul_i32 s7, s18, s20
	s_sub_i32 s5, s5, s7
	s_add_i32 s20, s19, s5
	s_cmp_ge_i32 s20, 64
	s_cselect_b32 s98, 6, 1
	s_add_i32 s18, s18, s98
	s_cmp_ge_i32 s18, 13
	s_cbranch_scc0 .Lrotb
	s_sub_i32 s18, s18, 13
.Lrotb:
.LBB0_136:
	s_ashr_i32 s21, s20, 31
	s_lshl_b64 s[22:23], s[20:21], 19
	s_add_u32 s22, s96, s22
	s_addc_u32 s23, s97, s23
	s_and_b64 s[24:25], s[0:1], exec
	s_cselect_b32 s5, s23, s27
	s_cselect_b32 s7, s22, s26
	s_ashr_i32 s19, s18, 31
	s_lshl_b64 s[24:25], s[18:19], 19
	s_add_u32 s24, s3, s24
	s_addc_u32 s25, s40, s25
	s_and_b64 s[30:31], s[0:1], exec
	s_cselect_b32 s19, s25, s29
	s_cselect_b32 s21, s24, s28
	s_add_u32 s26, s26, 0x40080
	s_addc_u32 s27, s27, 0
	s_add_u32 s34, s28, 0x100
	v_mov_b32_e32 v2, 0
	s_addc_u32 s35, s29, 0
	s_mov_b32 s36, -2
	v_mov_b32_e32 v3, v2
	v_mov_b32_e32 v4, v2
	v_mov_b32_e32 v5, v2
	v_mov_b32_e32 v6, v2
	v_mov_b32_e32 v7, v2
	v_mov_b32_e32 v8, v2
	v_mov_b32_e32 v9, v2
	v_mov_b32_e32 v10, v2
	v_mov_b32_e32 v11, v2
	v_mov_b32_e32 v12, v2
	v_mov_b32_e32 v13, v2
	v_mov_b32_e32 v14, v2
	v_mov_b32_e32 v15, v2
	v_mov_b32_e32 v16, v2
	v_mov_b32_e32 v17, v2
	v_mov_b32_e32 v18, v2
	v_mov_b32_e32 v19, v2
	v_mov_b32_e32 v20, v2
	v_mov_b32_e32 v21, v2
	v_mov_b32_e32 v22, v2
	v_mov_b32_e32 v23, v2
	v_mov_b32_e32 v24, v2
	v_mov_b32_e32 v25, v2
	v_mov_b32_e32 v26, v2
	v_mov_b32_e32 v27, v2
	v_mov_b32_e32 v28, v2
	v_mov_b32_e32 v29, v2
	v_mov_b32_e32 v30, v2
	v_mov_b32_e32 v31, v2
	v_mov_b32_e32 v32, v2
	v_mov_b32_e32 v33, v2
	v_mov_b32_e32 v66, v2
	v_mov_b32_e32 v67, v2
	v_mov_b32_e32 v68, v2
	v_mov_b32_e32 v69, v2
	v_mov_b32_e32 v70, v2
	v_mov_b32_e32 v71, v2
	v_mov_b32_e32 v72, v2
	v_mov_b32_e32 v73, v2
	v_mov_b32_e32 v74, v2
	v_mov_b32_e32 v75, v2
	v_mov_b32_e32 v76, v2
	v_mov_b32_e32 v77, v2
	v_mov_b32_e32 v78, v2
	v_mov_b32_e32 v79, v2
	v_mov_b32_e32 v80, v2
	v_mov_b32_e32 v81, v2
	v_mov_b32_e32 v82, v2
	v_mov_b32_e32 v83, v2
	v_mov_b32_e32 v84, v2
	v_mov_b32_e32 v85, v2
	v_mov_b32_e32 v86, v2
	v_mov_b32_e32 v87, v2
	v_mov_b32_e32 v88, v2
	v_mov_b32_e32 v89, v2
	v_mov_b32_e32 v90, v2
	v_mov_b32_e32 v91, v2
	v_mov_b32_e32 v92, v2
	v_mov_b32_e32 v93, v2
	v_mov_b32_e32 v94, v2
	v_mov_b32_e32 v95, v2
	v_mov_b32_e32 v96, v2
	v_mov_b32_e32 v97, v2
	v_mov_b32_e32 v34, v2
	v_mov_b32_e32 v35, v2
	v_mov_b32_e32 v36, v2
	v_mov_b32_e32 v37, v2
	v_mov_b32_e32 v38, v2
	v_mov_b32_e32 v39, v2
	v_mov_b32_e32 v40, v2
	v_mov_b32_e32 v41, v2
	v_mov_b32_e32 v42, v2
	v_mov_b32_e32 v43, v2
	v_mov_b32_e32 v44, v2
	v_mov_b32_e32 v45, v2
	v_mov_b32_e32 v46, v2
	v_mov_b32_e32 v47, v2
	v_mov_b32_e32 v48, v2
	v_mov_b32_e32 v49, v2
	v_mov_b32_e32 v50, v2
	v_mov_b32_e32 v51, v2
	v_mov_b32_e32 v52, v2
	v_mov_b32_e32 v53, v2
	v_mov_b32_e32 v54, v2
	v_mov_b32_e32 v55, v2
	v_mov_b32_e32 v56, v2
	v_mov_b32_e32 v57, v2
	v_mov_b32_e32 v58, v2
	v_mov_b32_e32 v59, v2
	v_mov_b32_e32 v60, v2
	v_mov_b32_e32 v61, v2
	v_mov_b32_e32 v62, v2
	v_mov_b32_e32 v63, v2
	v_mov_b32_e32 v64, v2
	v_mov_b32_e32 v65, v2
	v_mov_b32_e32 v98, v2
	v_mov_b32_e32 v99, v2
	v_mov_b32_e32 v100, v2
	v_mov_b32_e32 v101, v2
	v_mov_b32_e32 v102, v2
	v_mov_b32_e32 v103, v2
	v_mov_b32_e32 v104, v2
	v_mov_b32_e32 v105, v2
	v_mov_b32_e32 v106, v2
	v_mov_b32_e32 v107, v2
	v_mov_b32_e32 v108, v2
	v_mov_b32_e32 v109, v2
	v_mov_b32_e32 v110, v2
	v_mov_b32_e32 v111, v2
	v_mov_b32_e32 v112, v2
	v_mov_b32_e32 v113, v2
	v_mov_b32_e32 v114, v2
	v_mov_b32_e32 v115, v2
	v_mov_b32_e32 v116, v2
	v_mov_b32_e32 v117, v2
	v_mov_b32_e32 v118, v2
	v_mov_b32_e32 v119, v2
	v_mov_b32_e32 v120, v2
	v_mov_b32_e32 v121, v2
	v_mov_b32_e32 v122, v2
	v_mov_b32_e32 v123, v2
	v_mov_b32_e32 v124, v2
	v_mov_b32_e32 v125, v2
	v_mov_b32_e32 v126, v2
	v_mov_b32_e32 v127, v2
	v_mov_b32_e32 v128, v2
	v_mov_b32_e32 v129, v2
